# v4 + MLA staging: v_perm V^T packing, incremental 64-bit load addresses for tiles >= 3
# speedup vs baseline: 1.0356x; 1.0043x over previous
.LBB0_1496:
	s_mov_b32 s56, 0x5040100
	s_mov_b32 s57, 0x7060302
	s_waitcnt vmcnt(1)
	v_perm_b32 v108, v60, v52, s56
	v_perm_b32 v109, v60, v52, s57
	v_add_u32_e32 v110, 0x6800, v159
	ds_write_b128 v146, v[24:27]
	ds_write_b128 v147, v[28:31]
	ds_write_b128 v150, v[32:35]
	ds_write_b128 v151, v[36:39]
	ds_write_b128 v154, v[40:43]
	ds_write_b128 v158, v[48:51]
	ds_write2_b32 v110, v108, v109 offset1:68
	v_perm_b32 v108, v61, v53, s56
	v_perm_b32 v109, v61, v53, s57
	ds_write2_b32 v110, v108, v109 offset0:136 offset1:204
	v_perm_b32 v108, v62, v54, s56
	v_perm_b32 v109, v62, v54, s57
	v_add_u32_e32 v110, 0x6c00, v159
	ds_write2_b32 v110, v108, v109 offset0:16 offset1:84
	v_perm_b32 v108, v63, v55, s56
	v_perm_b32 v109, v63, v55, s57
	ds_write2_b32 v110, v108, v109 offset0:152 offset1:220
	s_waitcnt vmcnt(0)
	v_perm_b32 v108, v64, v56, s56
	v_perm_b32 v109, v64, v56, s57
	v_add_u32_e32 v110, 0x8800, v159
	ds_write2_b32 v110, v108, v109 offset0:128 offset1:196
	v_perm_b32 v108, v65, v57, s56
	v_perm_b32 v109, v65, v57, s57
	v_add_u32_e32 v110, 0x8c00, v159
	ds_write2_b32 v110, v108, v109 offset0:8 offset1:76
	v_perm_b32 v108, v66, v58, s56
	v_perm_b32 v109, v66, v58, s57
	ds_write2_b32 v110, v108, v109 offset0:144 offset1:212
	v_perm_b32 v108, v67, v59, s56
	v_perm_b32 v109, v67, v59, s57
	v_add_u32_e32 v110, 0x9000, v159
	s_mov_b64 s[20:21], -1
	s_mov_b64 s[16:17], 0
	s_cmp_lt_i32 s53, 33
	s_mov_b64 s[18:19], 0
	ds_write2_b32 v110, v108, v109 offset0:24 offset1:92
	s_waitcnt lgkmcnt(0)
	s_barrier
	s_cbranch_scc1 .Lmla_ld
	s_branch .LBB0_1483
.Lmla_ld:
	s_cmp_lt_u32 s53, 2
	s_cbranch_scc1 .Lmla_ld_slow
	s_mov_b64 s[54:55], 0x20000
	v_lshl_add_u64 v[112:113], v[112:113], 0, v[114:115]
	v_lshl_add_u64 v[118:119], v[118:119], 0, v[120:121]
	v_lshl_add_u64 v[122:123], v[122:123], 0, v[124:125]
	v_lshl_add_u64 v[126:127], v[126:127], 0, v[134:135]
	v_lshl_add_u64 v[136:137], v[136:137], 0, v[144:145]
	v_lshl_add_u64 v[140:141], v[140:141], 0, v[208:209]
	v_lshl_add_u64 v[138:139], v[138:139], 0, s[54:55]
	v_lshl_add_u64 v[142:143], v[142:143], 0, s[54:55]
	global_load_dwordx4 v[24:27], v[112:113], off
	global_load_dwordx4 v[28:31], v[118:119], off
	global_load_dwordx4 v[32:35], v[122:123], off
	global_load_dwordx4 v[36:39], v[126:127], off
	global_load_dwordx4 v[40:43], v[136:137], off
	global_load_dwordx4 v[48:51], v[140:141], off
	global_load_dwordx4 v[52:55], v[138:139], off offset:128
	global_load_dwordx4 v[56:59], v[138:139], off offset:192
	global_load_dwordx4 v[60:63], v[142:143], off offset:128
	global_load_dwordx4 v[64:67], v[142:143], off offset:192
	s_branch .LBB0_1483
.Lmla_ld_slow:
	v_mov_b32_e32 v108, v156
	s_cmp_eq_u32 s53, 0
	s_cbranch_scc1 .Lmla_ld_slow2
	v_lshl_add_u32 v108, s53, 7, v157
.Lmla_ld_slow2:
	v_add_u32_e32 v24, v108, v208
	v_add_u32_e32 v28, v108, v209
	v_add_u32_e32 v32, v108, v210
	v_add_u32_e32 v36, v108, v149
	v_add_u32_e32 v40, v108, v152
	v_add_u32_e32 v48, v108, v153
	v_add_u32_e32 v52, v108, v155
	v_ashrrev_i32_e32 v25, 31, v24
	v_ashrrev_i32_e32 v29, 31, v28
	v_ashrrev_i32_e32 v33, 31, v32
	v_ashrrev_i32_e32 v37, 31, v36
	v_ashrrev_i32_e32 v41, 31, v40
	v_ashrrev_i32_e32 v49, 31, v48
	v_ashrrev_i32_e32 v53, 31, v52
	v_lshlrev_b64 v[26:27], 10, v[24:25]
	v_lshlrev_b64 v[24:25], 12, v[24:25]
	v_lshlrev_b64 v[30:31], 10, v[28:29]
	v_lshlrev_b64 v[28:29], 12, v[28:29]
	v_lshlrev_b64 v[34:35], 10, v[32:33]
	v_lshlrev_b64 v[32:33], 12, v[32:33]
	v_lshlrev_b64 v[38:39], 10, v[36:37]
	v_lshlrev_b64 v[36:37], 12, v[36:37]
	v_lshlrev_b64 v[42:43], 10, v[40:41]
	v_lshlrev_b64 v[40:41], 12, v[40:41]
	v_lshlrev_b64 v[50:51], 10, v[48:49]
	v_lshlrev_b64 v[48:49], 12, v[48:49]
	v_lshlrev_b64 v[54:55], 10, v[52:53]
	v_add_u32_e32 v52, 1, v52
	v_lshl_add_u64 v[24:25], v[112:113], 0, v[24:25]
	v_lshl_add_u64 v[28:29], v[118:119], 0, v[28:29]
	v_lshl_add_u64 v[32:33], v[122:123], 0, v[32:33]
	v_lshl_add_u64 v[36:37], v[126:127], 0, v[36:37]
	v_lshl_add_u64 v[40:41], v[136:137], 0, v[40:41]
	v_lshl_add_u64 v[48:49], v[140:141], 0, v[48:49]
	v_ashrrev_i32_e32 v53, 31, v52
	v_lshl_add_u64 v[26:27], v[114:115], 0, v[26:27]
	v_lshl_add_u64 v[24:25], v[24:25], 0, s[70:71]
	v_lshl_add_u64 v[30:31], v[120:121], 0, v[30:31]
	v_lshl_add_u64 v[28:29], v[28:29], 0, s[70:71]
	v_lshl_add_u64 v[34:35], v[124:125], 0, v[34:35]
	v_lshl_add_u64 v[32:33], v[32:33], 0, s[70:71]
	v_lshl_add_u64 v[38:39], v[134:135], 0, v[38:39]
	v_lshl_add_u64 v[36:37], v[36:37], 0, s[70:71]
	v_lshl_add_u64 v[42:43], v[138:139], 0, v[42:43]
	v_lshl_add_u64 v[40:41], v[40:41], 0, s[70:71]
	v_lshl_add_u64 v[50:51], v[142:143], 0, v[50:51]
	v_lshl_add_u64 v[48:49], v[48:49], 0, s[70:71]
	v_lshlrev_b64 v[52:53], 10, v[52:53]
	v_cndmask_b32_e64 v25, v25, v27, s[4:5]
	v_cndmask_b32_e64 v24, v24, v26, s[4:5]
	v_cndmask_b32_e64 v29, v29, v31, s[6:7]
	v_cndmask_b32_e64 v28, v28, v30, s[6:7]
	v_cndmask_b32_e64 v33, v33, v35, s[8:9]
	v_cndmask_b32_e64 v32, v32, v34, s[8:9]
	v_cndmask_b32_e64 v37, v37, v39, s[10:11]
	v_cndmask_b32_e64 v36, v36, v38, s[10:11]
	v_cndmask_b32_e64 v41, v41, v43, s[12:13]
	v_cndmask_b32_e64 v40, v40, v42, s[12:13]
	v_cndmask_b32_e64 v49, v49, v51, s[14:15]
	v_cndmask_b32_e64 v48, v48, v50, s[14:15]
	v_lshl_add_u64 v[56:57], v[144:145], 0, v[54:55]
	v_lshl_add_u64 v[64:65], v[144:145], 0, v[52:53]
	s_cmp_eq_u32 s53, 1
	s_cbranch_scc0 .Lmla_ld_issue
	v_mov_b64_e32 v[112:113], v[24:25]
	v_mov_b64_e32 v[118:119], v[28:29]
	v_mov_b64_e32 v[122:123], v[32:33]
	v_mov_b64_e32 v[126:127], v[36:37]
	v_mov_b64_e32 v[136:137], v[40:41]
	v_mov_b64_e32 v[140:141], v[48:49]
	v_mov_b64_e32 v[138:139], v[56:57]
	v_mov_b64_e32 v[142:143], v[64:65]
	v_mov_b32_e32 v109, 0x80000
	v_mov_b32_e32 v110, 0x20000
	v_cndmask_b32_e64 v114, v109, v110, s[4:5]
	v_mov_b32_e32 v115, 0
	v_cndmask_b32_e64 v120, v109, v110, s[6:7]
	v_mov_b32_e32 v121, 0
	v_cndmask_b32_e64 v124, v109, v110, s[8:9]
	v_mov_b32_e32 v125, 0
	v_cndmask_b32_e64 v134, v109, v110, s[10:11]
	v_mov_b32_e32 v135, 0
	v_cndmask_b32_e64 v144, v109, v110, s[12:13]
	v_mov_b32_e32 v145, 0
	v_cndmask_b32_e64 v208, v109, v110, s[14:15]
	v_mov_b32_e32 v209, 0
.Lmla_ld_issue:
	global_load_dwordx4 v[24:27], v[24:25], off
	s_nop 0
	global_load_dwordx4 v[28:31], v[28:29], off
	s_nop 0
	global_load_dwordx4 v[32:35], v[32:33], off
	s_nop 0
	global_load_dwordx4 v[36:39], v[36:37], off
	s_nop 0
	global_load_dwordx4 v[40:43], v[40:41], off
	s_nop 0
	global_load_dwordx4 v[48:51], v[48:49], off
	s_nop 0
	global_load_dwordx4 v[52:55], v[56:57], off offset:128
	s_nop 0
	global_load_dwordx4 v[56:59], v[56:57], off offset:192
	s_nop 0
	global_load_dwordx4 v[60:63], v[64:65], off offset:128
	s_nop 0
	global_load_dwordx4 v[64:67], v[64:65], off offset:192
	s_branch .LBB0_1483
